# tile decode: float-division chain replaced by shifts (group size is 8 or 1) in five GEMM phases, on top of v24
# baseline (speedup 1.0000x reference)
.LBB0_253:
	s_ashr_i32 s12, s12, 3
	s_add_i32 s12, s53, s12
	s_mul_hi_i32 s50, s12, 0x78787879
	s_lshr_b32 s51, s50, 31
	s_ashr_i32 s50, s50, 6
	s_add_i32 s50, s50, s51
	s_lshl_b32 s52, s50, 3
	s_sub_i32 s51, 0x101, s52
	s_min_u32 s53, s51, 8
	s_mulk_i32 s50, 0x88
	s_sub_i32 s12, s12, s50
	s_cmp_eq_u32 s53, 8
	s_cselect_b32 s54, 3, 0
	s_lshr_b32 s50, s12, s54
	s_lshl_b32 s51, s50, s54
	s_sub_i32 s12, s12, s51
	s_add_i32 s52, s52, s12

.LBB0_1105:
	s_ashr_i32 s9, s9, 3
	s_add_i32 s9, s23, s9
	s_ashr_i32 s20, s9, 31
	s_lshr_b32 s20, s20, 27
	s_add_i32 s20, s9, s20
	s_ashr_i32 s21, s20, 5
	s_lshl_b32 s22, s21, 3
	s_sub_i32 s21, 0x101, s22
	s_min_u32 s23, s21, 8
	s_andn2_b32 s20, s20, 31
	s_sub_i32 s9, s9, s20
	s_cmp_eq_u32 s23, 8
	s_cselect_b32 s24, 3, 0
	s_lshr_b32 s20, s9, s24
	s_lshl_b32 s21, s20, s24
	s_sub_i32 s9, s9, s21
	s_add_i32 s22, s22, s9
	s_and_b32 s53, s52, 1

.LBB0_1278:
	s_ashr_i32 s11, s11, 3
	s_add_i32 s11, s34, s11
	s_ashr_i32 s13, s11, 31
	s_lshr_b32 s13, s13, 27
	s_add_i32 s13, s11, s13
	s_ashr_i32 s30, s13, 5
	s_lshl_b32 s34, s30, 3
	s_sub_i32 s30, 0x101, s34
	s_min_u32 s35, s30, 8
	s_andn2_b32 s13, s13, 31
	s_sub_i32 s11, s11, s13
	s_waitcnt lgkmcnt(0)
	s_cmp_eq_u32 s35, 8
	s_cselect_b32 s13, 3, 0
	s_lshr_b32 s30, s11, s13
	s_lshl_b32 s13, s30, s13
	s_sub_i32 s11, s11, s13
	s_add_i32 s34, s34, s11

.LBB0_1369:
	s_ashr_i32 s16, s18, 3
	s_add_i32 s16, s20, s16
	s_mul_hi_i32 s17, s16, 0x2e8ba2e9
	s_lshr_b32 s18, s17, 31
	s_ashr_i32 s17, s17, 5
	s_add_i32 s17, s17, s18
	s_lshl_b32 s18, s17, 3
	s_sub_i32 s19, 0x101, s18
	s_min_u32 s19, s19, 8
	s_mulk_i32 s17, 0xb0
	s_sub_i32 s20, s16, s17
	s_cmp_eq_u32 s19, 8
	s_cselect_b32 s21, 3, 0
	s_lshr_b32 s16, s20, s21
	s_lshl_b32 s17, s16, s21
	s_sub_i32 s17, s20, s17
	s_add_i32 s18, s18, s17

.LBB0_1441:
	s_ashr_i32 s0, s16, 3
	s_add_i32 s0, s18, s0
	s_ashr_i32 s1, s0, 31
	s_lshr_b32 s1, s1, 27
	s_add_i32 s1, s0, s1
	s_ashr_i32 s16, s1, 5
	s_lshl_b32 s16, s16, 3
	s_sub_i32 s17, 0x101, s16
	s_min_u32 s17, s17, 8
	s_andn2_b32 s1, s1, 31
	s_sub_i32 s18, s0, s1
	s_cmp_eq_u32 s17, 8
	s_cselect_b32 s19, 3, 0
	s_lshr_b32 s44, s18, s19
	s_lshl_b32 s0, s44, s19
	s_sub_i32 s0, s18, s0
	s_add_i32 s45, s16, s0
